# attention unit prologue: Q-fragment waits count the LDS-DMA loads issued behind them (vmcnt 10/8 instead of 2/0), so the first K/V tiles stay in flight during block selection
# speedup vs baseline: 1.0032x; 1.0032x over previous
.LBB0_344:
	v_and_b32_e32 v51, 63, v16
	s_cmp_eq_u32 s69, 0
	v_lshlrev_b32_e32 v18, 2, v51
	s_cselect_b64 s[52:53], -1, 0
	v_lshl_add_u32 v54, v50, 5, s39
	v_xor_b32_e32 v105, 0x80, v18
	v_mov_b32_e32 v52, 0xff800000
	s_and_b64 vcc, exec, s[52:53]
	s_waitcnt vmcnt(10)
	v_lshlrev_b32_e32 v47, 16, v4
	v_lshlrev_b32_e32 v46, 16, v0
	v_and_b32_e32 v49, 0xffff0000, v4
	v_and_b32_e32 v48, 0xffff0000, v0
	v_lshlrev_b32_e32 v45, 16, v5
	v_lshlrev_b32_e32 v44, 16, v1
	v_and_b32_e32 v43, 0xffff0000, v5
	v_and_b32_e32 v42, 0xffff0000, v1
	v_lshlrev_b32_e32 v41, 16, v6
	v_lshlrev_b32_e32 v40, 16, v2
	v_and_b32_e32 v39, 0xffff0000, v6
	v_and_b32_e32 v38, 0xffff0000, v2
	v_lshlrev_b32_e32 v37, 16, v7
	v_lshlrev_b32_e32 v36, 16, v3
	v_and_b32_e32 v35, 0xffff0000, v7
	v_and_b32_e32 v34, 0xffff0000, v3
	s_waitcnt vmcnt(8)
	v_lshlrev_b32_e32 v31, 16, v12
	v_lshlrev_b32_e32 v30, 16, v8
	v_and_b32_e32 v33, 0xffff0000, v12
	v_and_b32_e32 v32, 0xffff0000, v8
	v_lshlrev_b32_e32 v29, 16, v13
	v_lshlrev_b32_e32 v28, 16, v9
	v_and_b32_e32 v27, 0xffff0000, v13
	v_and_b32_e32 v26, 0xffff0000, v9
	v_lshlrev_b32_e32 v25, 16, v14
	v_lshlrev_b32_e32 v24, 16, v10
	v_and_b32_e32 v23, 0xffff0000, v14
	v_and_b32_e32 v22, 0xffff0000, v10
	v_lshlrev_b32_e32 v21, 16, v15
	v_lshlrev_b32_e32 v20, 16, v11
	v_and_b32_e32 v19, 0xffff0000, v15
	v_and_b32_e32 v18, 0xffff0000, v11
	v_mov_b32_e32 v53, 0xff800000
	s_waitcnt lgkmcnt(0)
	s_barrier
	s_cbranch_vccnz .LBB0_350
	ds_read_b128 v[56:59], v54
	ds_read_b128 v[60:63], v54 offset:128
	ds_read_b128 v[64:67], v54 offset:16
	ds_read_b128 v[68:71], v54 offset:144
	s_waitcnt lgkmcnt(3)
	v_mov_b32_e32 v72, v56
	s_waitcnt lgkmcnt(2)
	v_mov_b32_e32 v73, v60
	v_mov_b32_e32 v60, v57
	v_pk_mul_f32 v[56:57], v[60:61], v[48:49]
	v_mov_b32_e32 v60, v58
	v_pk_fma_f32 v[56:57], v[72:73], v[46:47], v[56:57]
	v_mov_b32_e32 v61, v62
	v_pk_fma_f32 v[56:57], v[60:61], v[44:45], v[56:57]
	v_mov_b32_e32 v62, v59
	v_pk_fma_f32 v[56:57], v[62:63], v[42:43], v[56:57]
	s_waitcnt lgkmcnt(1)
	v_mov_b32_e32 v58, v64
	s_waitcnt lgkmcnt(0)
	v_mov_b32_e32 v59, v68
	v_pk_fma_f32 v[56:57], v[58:59], v[40:41], v[56:57]
	v_mov_b32_e32 v68, v65
	v_pk_fma_f32 v[56:57], v[68:69], v[38:39], v[56:57]
	v_mov_b32_e32 v58, v66
	v_mov_b32_e32 v59, v70
	v_pk_fma_f32 v[56:57], v[58:59], v[36:37], v[56:57]
	v_mov_b32_e32 v70, v67
	v_pk_fma_f32 v[64:65], v[70:71], v[34:35], v[56:57]
	ds_read_b128 v[56:59], v54 offset:256
	ds_read_b128 v[60:63], v54 offset:384
	v_add_f32_e32 v53, 0, v64
	v_add_f32_e32 v53, v53, v65
	ds_read_b128 v[64:67], v54 offset:272
	ds_read_b128 v[68:71], v54 offset:400
	s_waitcnt lgkmcnt(3)
	v_mov_b32_e32 v72, v56
	s_waitcnt lgkmcnt(2)
	v_mov_b32_e32 v73, v60
	v_mov_b32_e32 v60, v57
	v_pk_mul_f32 v[56:57], v[60:61], v[32:33]
	v_mov_b32_e32 v60, v58
	v_pk_fma_f32 v[56:57], v[72:73], v[30:31], v[56:57]
	v_mov_b32_e32 v61, v62
	v_pk_fma_f32 v[56:57], v[60:61], v[28:29], v[56:57]
	v_mov_b32_e32 v62, v59
	v_pk_fma_f32 v[56:57], v[62:63], v[26:27], v[56:57]
	s_waitcnt lgkmcnt(1)
	v_mov_b32_e32 v58, v64
	s_waitcnt lgkmcnt(0)
	v_mov_b32_e32 v59, v68
	v_pk_fma_f32 v[56:57], v[58:59], v[24:25], v[56:57]
	v_mov_b32_e32 v68, v65
	v_pk_fma_f32 v[56:57], v[68:69], v[22:23], v[56:57]
	v_mov_b32_e32 v58, v66
	v_mov_b32_e32 v59, v70
	v_pk_fma_f32 v[56:57], v[58:59], v[20:21], v[56:57]
	v_mov_b32_e32 v70, v67
	v_pk_fma_f32 v[56:57], v[70:71], v[18:19], v[56:57]
	s_nop 0
	v_add_f32_e32 v53, v53, v56
	v_add_f32_e32 v53, v53, v57
	ds_swizzle_b32 v55, v53 offset:swizzle(SWAP,16)
	s_waitcnt lgkmcnt(0)
	v_add_f32_e32 v53, v53, v55
	ds_bpermute_b32 v55, v105, v53
	s_waitcnt lgkmcnt(0)
	v_add_f32_e32 v53, v53, v55
	s_cmp_lt_u32 s69, 2
	s_cbranch_scc0 .LBB0_351

.LBB0_398:
	v_and_b32_e32 v19, 63, v16
	v_lshlrev_b32_e32 v20, 2, v19
	v_lshl_add_u32 v22, v18, 5, s39
	v_xor_b32_e32 v105, 0x80, v20
	v_mov_b32_e32 v20, 0xff800000
	s_andn2_b64 vcc, exec, s[62:63]
	v_mov_b32_e32 v21, 0xff800000
	s_waitcnt lgkmcnt(0)
	s_barrier
	s_cbranch_vccnz .LBB0_404
	ds_read_b128 v[24:27], v22
	ds_read_b128 v[28:31], v22 offset:16
	ds_read_b128 v[32:35], v22 offset:128
	ds_read_b128 v[36:39], v22 offset:144
	s_waitcnt vmcnt(10)
	v_and_b32_e32 v45, 0xffff0000, v4
	v_and_b32_e32 v44, 0xffff0000, v0
	v_lshlrev_b32_e32 v41, 16, v4
	s_waitcnt lgkmcnt(1)
	v_mov_b32_e32 v43, v32
	v_mov_b32_e32 v32, v25
	v_lshlrev_b32_e32 v40, 16, v0
	v_mov_b32_e32 v42, v24
	v_pk_mul_f32 v[24:25], v[32:33], v[44:45]
	v_lshlrev_b32_e32 v33, 16, v5
	v_pk_fma_f32 v[24:25], v[42:43], v[40:41], v[24:25]
	v_lshlrev_b32_e32 v32, 16, v1
	v_mov_b32_e32 v40, v26
	v_mov_b32_e32 v41, v34
	v_pk_fma_f32 v[24:25], v[40:41], v[32:33], v[24:25]
	v_and_b32_e32 v33, 0xffff0000, v5
	v_and_b32_e32 v32, 0xffff0000, v1
	v_mov_b32_e32 v34, v27
	v_pk_fma_f32 v[24:25], v[34:35], v[32:33], v[24:25]
	v_lshlrev_b32_e32 v27, 16, v6
	v_lshlrev_b32_e32 v26, 16, v2
	v_mov_b32_e32 v32, v28
	s_waitcnt lgkmcnt(0)
	v_mov_b32_e32 v33, v36
	v_pk_fma_f32 v[24:25], v[32:33], v[26:27], v[24:25]
	v_and_b32_e32 v27, 0xffff0000, v6
	v_and_b32_e32 v26, 0xffff0000, v2
	v_mov_b32_e32 v36, v29
	v_pk_fma_f32 v[24:25], v[36:37], v[26:27], v[24:25]
	v_lshlrev_b32_e32 v27, 16, v7
	v_lshlrev_b32_e32 v26, 16, v3
	v_mov_b32_e32 v28, v30
	v_mov_b32_e32 v29, v38
	v_pk_fma_f32 v[24:25], v[28:29], v[26:27], v[24:25]
	v_and_b32_e32 v27, 0xffff0000, v7
	v_and_b32_e32 v26, 0xffff0000, v3
	v_mov_b32_e32 v38, v31
	v_pk_fma_f32 v[24:25], v[38:39], v[26:27], v[24:25]
	s_waitcnt vmcnt(8)
	v_and_b32_e32 v45, 0xffff0000, v12
	v_add_f32_e32 v21, 0, v24
	v_add_f32_e32 v21, v21, v25
	ds_read_b128 v[24:27], v22 offset:256
	ds_read_b128 v[28:31], v22 offset:272
	ds_read_b128 v[32:35], v22 offset:384
	ds_read_b128 v[36:39], v22 offset:400
	v_and_b32_e32 v44, 0xffff0000, v8
	v_lshlrev_b32_e32 v41, 16, v12
	v_lshlrev_b32_e32 v40, 16, v8
	s_waitcnt lgkmcnt(1)
	v_mov_b32_e32 v43, v32
	v_mov_b32_e32 v32, v25
	v_mov_b32_e32 v42, v24
	v_pk_mul_f32 v[24:25], v[32:33], v[44:45]
	v_lshlrev_b32_e32 v33, 16, v13
	v_pk_fma_f32 v[24:25], v[42:43], v[40:41], v[24:25]
	v_lshlrev_b32_e32 v32, 16, v9
	v_mov_b32_e32 v40, v26
	v_mov_b32_e32 v41, v34
	v_pk_fma_f32 v[24:25], v[40:41], v[32:33], v[24:25]
	v_and_b32_e32 v33, 0xffff0000, v13
	v_and_b32_e32 v32, 0xffff0000, v9
	v_mov_b32_e32 v34, v27
	v_pk_fma_f32 v[24:25], v[34:35], v[32:33], v[24:25]
	v_lshlrev_b32_e32 v27, 16, v14
	v_lshlrev_b32_e32 v26, 16, v10
	v_mov_b32_e32 v32, v28
	s_waitcnt lgkmcnt(0)
	v_mov_b32_e32 v33, v36
	v_pk_fma_f32 v[24:25], v[32:33], v[26:27], v[24:25]
	v_and_b32_e32 v27, 0xffff0000, v14
	v_and_b32_e32 v26, 0xffff0000, v10
	v_mov_b32_e32 v36, v29
	v_pk_fma_f32 v[24:25], v[36:37], v[26:27], v[24:25]
	v_lshlrev_b32_e32 v27, 16, v15
	v_lshlrev_b32_e32 v26, 16, v11
	v_mov_b32_e32 v28, v30
	v_mov_b32_e32 v29, v38
	v_pk_fma_f32 v[24:25], v[28:29], v[26:27], v[24:25]
	v_and_b32_e32 v27, 0xffff0000, v15
	v_and_b32_e32 v26, 0xffff0000, v11
	v_mov_b32_e32 v38, v31
	v_pk_fma_f32 v[24:25], v[38:39], v[26:27], v[24:25]
	s_nop 0
	v_add_f32_e32 v21, v21, v24
	v_add_f32_e32 v21, v21, v25
	ds_swizzle_b32 v23, v21 offset:swizzle(SWAP,16)
	s_waitcnt lgkmcnt(0)
	v_add_f32_e32 v21, v21, v23
	ds_bpermute_b32 v23, v105, v21
	s_waitcnt lgkmcnt(0)
	v_add_f32_e32 v21, v21, v23
	s_cmp_lt_u32 s80, 2
	s_cbranch_scc0 .LBB0_405

.LBB0_401:
	ds_read_b128 v[24:27], v22 offset:1024
	ds_read_b128 v[28:31], v22 offset:1040
	ds_read_b128 v[32:35], v22 offset:1152
	ds_read_b128 v[36:39], v22 offset:1168
	s_waitcnt vmcnt(10)
	v_and_b32_e32 v45, 0xffff0000, v4
	v_and_b32_e32 v44, 0xffff0000, v0
	v_lshlrev_b32_e32 v41, 16, v4
	s_waitcnt lgkmcnt(1)
	v_mov_b32_e32 v43, v32
	v_mov_b32_e32 v32, v25
	v_lshlrev_b32_e32 v40, 16, v0
	v_mov_b32_e32 v42, v24
	v_pk_mul_f32 v[24:25], v[32:33], v[44:45]
	v_lshlrev_b32_e32 v33, 16, v5
	v_pk_fma_f32 v[24:25], v[42:43], v[40:41], v[24:25]
	v_lshlrev_b32_e32 v32, 16, v1
	v_mov_b32_e32 v40, v26
	v_mov_b32_e32 v41, v34
	v_pk_fma_f32 v[24:25], v[40:41], v[32:33], v[24:25]
	v_and_b32_e32 v33, 0xffff0000, v5
	v_and_b32_e32 v32, 0xffff0000, v1
	v_mov_b32_e32 v34, v27
	v_pk_fma_f32 v[24:25], v[34:35], v[32:33], v[24:25]
	v_lshlrev_b32_e32 v27, 16, v6
	v_lshlrev_b32_e32 v26, 16, v2
	v_mov_b32_e32 v32, v28
	s_waitcnt lgkmcnt(0)
	v_mov_b32_e32 v33, v36
	v_pk_fma_f32 v[24:25], v[32:33], v[26:27], v[24:25]
	v_and_b32_e32 v27, 0xffff0000, v6
	v_and_b32_e32 v26, 0xffff0000, v2
	v_mov_b32_e32 v36, v29
	v_pk_fma_f32 v[24:25], v[36:37], v[26:27], v[24:25]
	v_lshlrev_b32_e32 v27, 16, v7
	v_lshlrev_b32_e32 v26, 16, v3
	v_mov_b32_e32 v28, v30
	v_mov_b32_e32 v29, v38
	v_pk_fma_f32 v[24:25], v[28:29], v[26:27], v[24:25]
	v_and_b32_e32 v27, 0xffff0000, v7
	v_and_b32_e32 v26, 0xffff0000, v3
	v_mov_b32_e32 v38, v31
	v_pk_fma_f32 v[24:25], v[38:39], v[26:27], v[24:25]
	s_waitcnt vmcnt(8)
	v_and_b32_e32 v45, 0xffff0000, v12
	v_add_f32_e32 v24, 0, v24
	v_add_f32_e32 v46, v24, v25
	ds_read_b128 v[24:27], v22 offset:1280
	ds_read_b128 v[28:31], v22 offset:1296
	ds_read_b128 v[32:35], v22 offset:1408
	ds_read_b128 v[36:39], v22 offset:1424
	v_and_b32_e32 v44, 0xffff0000, v8
	v_lshlrev_b32_e32 v41, 16, v12
	v_lshlrev_b32_e32 v40, 16, v8
	s_waitcnt lgkmcnt(1)
	v_mov_b32_e32 v43, v32
	v_mov_b32_e32 v32, v25
	v_mov_b32_e32 v42, v24
	v_pk_mul_f32 v[24:25], v[32:33], v[44:45]
	v_lshlrev_b32_e32 v33, 16, v13
	v_pk_fma_f32 v[24:25], v[42:43], v[40:41], v[24:25]
	v_lshlrev_b32_e32 v32, 16, v9
	v_mov_b32_e32 v40, v26
	v_mov_b32_e32 v41, v34
	v_pk_fma_f32 v[24:25], v[40:41], v[32:33], v[24:25]
	v_and_b32_e32 v33, 0xffff0000, v13
	v_and_b32_e32 v32, 0xffff0000, v9
	v_mov_b32_e32 v34, v27
	v_pk_fma_f32 v[24:25], v[34:35], v[32:33], v[24:25]
	v_lshlrev_b32_e32 v27, 16, v14
	v_lshlrev_b32_e32 v26, 16, v10
	v_mov_b32_e32 v32, v28
	s_waitcnt lgkmcnt(0)
	v_mov_b32_e32 v33, v36
	v_pk_fma_f32 v[24:25], v[32:33], v[26:27], v[24:25]
	v_and_b32_e32 v27, 0xffff0000, v14
	v_and_b32_e32 v26, 0xffff0000, v10
	v_mov_b32_e32 v36, v29
	v_pk_fma_f32 v[24:25], v[36:37], v[26:27], v[24:25]
	v_lshlrev_b32_e32 v27, 16, v15
	v_lshlrev_b32_e32 v26, 16, v11
	v_mov_b32_e32 v28, v30
	v_mov_b32_e32 v29, v38
	v_pk_fma_f32 v[24:25], v[28:29], v[26:27], v[24:25]
	v_and_b32_e32 v27, 0xffff0000, v15
	v_and_b32_e32 v26, 0xffff0000, v11
	v_mov_b32_e32 v38, v31
	v_pk_fma_f32 v[24:25], v[38:39], v[26:27], v[24:25]
	s_nop 0
	v_add_f32_e32 v24, v46, v24
	v_add_f32_e32 v24, v24, v25
	ds_swizzle_b32 v25, v24 offset:swizzle(SWAP,16)
	s_waitcnt lgkmcnt(0)
	v_add_f32_e32 v24, v24, v25
	ds_bpermute_b32 v25, v105, v24
	s_waitcnt lgkmcnt(0)
	v_add_f32_e32 v24, v24, v25
	s_cmp_lt_u32 s80, 4
	s_cbranch_scc0 .LBB0_407

.LBB0_403:
	ds_read_b128 v[26:29], v22 offset:2048
	ds_read_b128 v[30:33], v22 offset:2064
	ds_read_b128 v[34:37], v22 offset:2176
	ds_read_b128 v[38:41], v22 offset:2192
	s_waitcnt vmcnt(10)
	v_and_b32_e32 v47, 0xffff0000, v4
	v_and_b32_e32 v46, 0xffff0000, v0
	v_lshlrev_b32_e32 v43, 16, v4
	s_waitcnt lgkmcnt(1)
	v_mov_b32_e32 v45, v34
	v_mov_b32_e32 v34, v27
	v_lshlrev_b32_e32 v42, 16, v0
	v_mov_b32_e32 v44, v26
	v_pk_mul_f32 v[26:27], v[34:35], v[46:47]
	v_lshlrev_b32_e32 v35, 16, v5
	v_pk_fma_f32 v[26:27], v[44:45], v[42:43], v[26:27]
	v_lshlrev_b32_e32 v34, 16, v1
	v_mov_b32_e32 v42, v28
	v_mov_b32_e32 v43, v36
	v_pk_fma_f32 v[26:27], v[42:43], v[34:35], v[26:27]
	v_and_b32_e32 v35, 0xffff0000, v5
	v_and_b32_e32 v34, 0xffff0000, v1
	v_mov_b32_e32 v36, v29
	v_pk_fma_f32 v[26:27], v[36:37], v[34:35], v[26:27]
	v_lshlrev_b32_e32 v29, 16, v6
	v_lshlrev_b32_e32 v28, 16, v2
	v_mov_b32_e32 v34, v30
	s_waitcnt lgkmcnt(0)
	v_mov_b32_e32 v35, v38
	v_pk_fma_f32 v[26:27], v[34:35], v[28:29], v[26:27]
	v_and_b32_e32 v29, 0xffff0000, v6
	v_and_b32_e32 v28, 0xffff0000, v2
	v_mov_b32_e32 v38, v31
	v_pk_fma_f32 v[26:27], v[38:39], v[28:29], v[26:27]
	v_lshlrev_b32_e32 v29, 16, v7
	v_lshlrev_b32_e32 v28, 16, v3
	v_mov_b32_e32 v30, v32
	v_mov_b32_e32 v31, v40
	v_pk_fma_f32 v[26:27], v[30:31], v[28:29], v[26:27]
	v_and_b32_e32 v29, 0xffff0000, v7
	v_and_b32_e32 v28, 0xffff0000, v3
	v_mov_b32_e32 v40, v33
	v_pk_fma_f32 v[26:27], v[40:41], v[28:29], v[26:27]
	s_waitcnt vmcnt(8)
	v_and_b32_e32 v47, 0xffff0000, v12
	v_add_f32_e32 v26, 0, v26
	v_add_f32_e32 v48, v26, v27
	ds_read_b128 v[26:29], v22 offset:2304
	ds_read_b128 v[30:33], v22 offset:2320
	ds_read_b128 v[34:37], v22 offset:2432
	ds_read_b128 v[38:41], v22 offset:2448
	v_and_b32_e32 v46, 0xffff0000, v8
	v_lshlrev_b32_e32 v43, 16, v12
	v_lshlrev_b32_e32 v42, 16, v8
	s_waitcnt lgkmcnt(1)
	v_mov_b32_e32 v45, v34
	v_mov_b32_e32 v34, v27
	v_mov_b32_e32 v44, v26
	v_pk_mul_f32 v[26:27], v[34:35], v[46:47]
	v_lshlrev_b32_e32 v35, 16, v13
	v_pk_fma_f32 v[26:27], v[44:45], v[42:43], v[26:27]
	v_lshlrev_b32_e32 v34, 16, v9
	v_mov_b32_e32 v42, v28
	v_mov_b32_e32 v43, v36
	v_pk_fma_f32 v[26:27], v[42:43], v[34:35], v[26:27]
	v_and_b32_e32 v35, 0xffff0000, v13
	v_and_b32_e32 v34, 0xffff0000, v9
	v_mov_b32_e32 v36, v29
	v_pk_fma_f32 v[26:27], v[36:37], v[34:35], v[26:27]
	v_lshlrev_b32_e32 v29, 16, v14
	v_lshlrev_b32_e32 v28, 16, v10
	v_mov_b32_e32 v34, v30
	s_waitcnt lgkmcnt(0)
	v_mov_b32_e32 v35, v38
	v_pk_fma_f32 v[26:27], v[34:35], v[28:29], v[26:27]
	v_and_b32_e32 v29, 0xffff0000, v14
	v_and_b32_e32 v28, 0xffff0000, v10
	v_mov_b32_e32 v38, v31
	v_pk_fma_f32 v[26:27], v[38:39], v[28:29], v[26:27]
	v_lshlrev_b32_e32 v29, 16, v15
	v_lshlrev_b32_e32 v28, 16, v11
	v_mov_b32_e32 v30, v32
	v_mov_b32_e32 v31, v40
	v_pk_fma_f32 v[26:27], v[30:31], v[28:29], v[26:27]
	v_and_b32_e32 v29, 0xffff0000, v15
	v_and_b32_e32 v28, 0xffff0000, v11
	v_mov_b32_e32 v40, v33
	v_pk_fma_f32 v[26:27], v[40:41], v[28:29], v[26:27]
	s_nop 0
	v_add_f32_e32 v26, v48, v26
	v_add_f32_e32 v26, v26, v27
	ds_swizzle_b32 v27, v26 offset:swizzle(SWAP,16)
	s_waitcnt lgkmcnt(0)
	v_add_f32_e32 v26, v26, v27
	ds_bpermute_b32 v27, v105, v26
	s_waitcnt lgkmcnt(0)
	v_add_f32_e32 v26, v26, v27
	s_cmp_lt_u32 s80, 6
	s_cbranch_scc0 .LBB0_409
	s_branch .LBB0_410

.LBB0_405:
	ds_read_b128 v[24:27], v22 offset:512
	ds_read_b128 v[28:31], v22 offset:528
	ds_read_b128 v[32:35], v22 offset:640
	ds_read_b128 v[36:39], v22 offset:656
	s_waitcnt vmcnt(10)
	v_and_b32_e32 v45, 0xffff0000, v4
	v_and_b32_e32 v44, 0xffff0000, v0
	v_lshlrev_b32_e32 v41, 16, v4
	s_waitcnt lgkmcnt(1)
	v_mov_b32_e32 v43, v32
	v_mov_b32_e32 v32, v25
	v_lshlrev_b32_e32 v40, 16, v0
	v_mov_b32_e32 v42, v24
	v_pk_mul_f32 v[24:25], v[32:33], v[44:45]
	v_lshlrev_b32_e32 v33, 16, v5
	v_pk_fma_f32 v[24:25], v[42:43], v[40:41], v[24:25]
	v_lshlrev_b32_e32 v32, 16, v1
	v_mov_b32_e32 v40, v26
	v_mov_b32_e32 v41, v34
	v_pk_fma_f32 v[24:25], v[40:41], v[32:33], v[24:25]
	v_and_b32_e32 v33, 0xffff0000, v5
	v_and_b32_e32 v32, 0xffff0000, v1
	v_mov_b32_e32 v34, v27
	v_pk_fma_f32 v[24:25], v[34:35], v[32:33], v[24:25]
	v_lshlrev_b32_e32 v27, 16, v6
	v_lshlrev_b32_e32 v26, 16, v2
	v_mov_b32_e32 v32, v28
	s_waitcnt lgkmcnt(0)
	v_mov_b32_e32 v33, v36
	v_pk_fma_f32 v[24:25], v[32:33], v[26:27], v[24:25]
	v_and_b32_e32 v27, 0xffff0000, v6
	v_and_b32_e32 v26, 0xffff0000, v2
	v_mov_b32_e32 v36, v29
	v_pk_fma_f32 v[24:25], v[36:37], v[26:27], v[24:25]
	v_lshlrev_b32_e32 v27, 16, v7
	v_lshlrev_b32_e32 v26, 16, v3
	v_mov_b32_e32 v28, v30
	v_mov_b32_e32 v29, v38
	v_pk_fma_f32 v[24:25], v[28:29], v[26:27], v[24:25]
	v_and_b32_e32 v27, 0xffff0000, v7
	v_and_b32_e32 v26, 0xffff0000, v3
	v_mov_b32_e32 v38, v31
	v_pk_fma_f32 v[24:25], v[38:39], v[26:27], v[24:25]
	s_waitcnt vmcnt(8)
	v_and_b32_e32 v45, 0xffff0000, v12
	v_add_f32_e32 v20, 0, v24
	v_add_f32_e32 v20, v20, v25
	ds_read_b128 v[24:27], v22 offset:768
	ds_read_b128 v[28:31], v22 offset:784
	ds_read_b128 v[32:35], v22 offset:896
	ds_read_b128 v[36:39], v22 offset:912
	v_and_b32_e32 v44, 0xffff0000, v8
	v_lshlrev_b32_e32 v41, 16, v12
	v_lshlrev_b32_e32 v40, 16, v8
	s_waitcnt lgkmcnt(1)
	v_mov_b32_e32 v43, v32
	v_mov_b32_e32 v32, v25
	v_mov_b32_e32 v42, v24
	v_pk_mul_f32 v[24:25], v[32:33], v[44:45]
	v_lshlrev_b32_e32 v33, 16, v13
	v_pk_fma_f32 v[24:25], v[42:43], v[40:41], v[24:25]
	v_lshlrev_b32_e32 v32, 16, v9
	v_mov_b32_e32 v40, v26
	v_mov_b32_e32 v41, v34
	v_pk_fma_f32 v[24:25], v[40:41], v[32:33], v[24:25]
	v_and_b32_e32 v33, 0xffff0000, v13
	v_and_b32_e32 v32, 0xffff0000, v9
	v_mov_b32_e32 v34, v27
	v_pk_fma_f32 v[24:25], v[34:35], v[32:33], v[24:25]
	v_lshlrev_b32_e32 v27, 16, v14
	v_lshlrev_b32_e32 v26, 16, v10
	v_mov_b32_e32 v32, v28
	s_waitcnt lgkmcnt(0)
	v_mov_b32_e32 v33, v36
	v_pk_fma_f32 v[24:25], v[32:33], v[26:27], v[24:25]
	v_and_b32_e32 v27, 0xffff0000, v14
	v_and_b32_e32 v26, 0xffff0000, v10
	v_mov_b32_e32 v36, v29
	v_pk_fma_f32 v[24:25], v[36:37], v[26:27], v[24:25]
	v_lshlrev_b32_e32 v27, 16, v15
	v_lshlrev_b32_e32 v26, 16, v11
	v_mov_b32_e32 v28, v30
	v_mov_b32_e32 v29, v38
	v_pk_fma_f32 v[24:25], v[28:29], v[26:27], v[24:25]
	v_and_b32_e32 v27, 0xffff0000, v15
	v_and_b32_e32 v26, 0xffff0000, v11
	v_mov_b32_e32 v38, v31
	v_pk_fma_f32 v[24:25], v[38:39], v[26:27], v[24:25]
	s_nop 0
	v_add_f32_e32 v20, v20, v24
	v_add_f32_e32 v20, v20, v25
	ds_swizzle_b32 v23, v20 offset:swizzle(SWAP,16)
	s_waitcnt lgkmcnt(0)
	v_add_f32_e32 v20, v20, v23
	ds_bpermute_b32 v23, v105, v20
	s_waitcnt lgkmcnt(0)
	v_add_f32_e32 v20, v20, v23
	v_mov_b32_e32 v23, 0xff800000
	s_cmp_lt_u32 s80, 3
	v_mov_b32_e32 v24, 0xff800000
	s_cbranch_scc0 .LBB0_401

.LBB0_407:
	ds_read_b128 v[26:29], v22 offset:1536
	ds_read_b128 v[30:33], v22 offset:1552
	ds_read_b128 v[34:37], v22 offset:1664
	ds_read_b128 v[38:41], v22 offset:1680
	s_waitcnt vmcnt(10)
	v_and_b32_e32 v47, 0xffff0000, v4
	v_and_b32_e32 v46, 0xffff0000, v0
	v_lshlrev_b32_e32 v43, 16, v4
	s_waitcnt lgkmcnt(1)
	v_mov_b32_e32 v45, v34
	v_mov_b32_e32 v34, v27
	v_lshlrev_b32_e32 v42, 16, v0
	v_mov_b32_e32 v44, v26
	v_pk_mul_f32 v[26:27], v[34:35], v[46:47]
	v_lshlrev_b32_e32 v35, 16, v5
	v_pk_fma_f32 v[26:27], v[44:45], v[42:43], v[26:27]
	v_lshlrev_b32_e32 v34, 16, v1
	v_mov_b32_e32 v42, v28
	v_mov_b32_e32 v43, v36
	v_pk_fma_f32 v[26:27], v[42:43], v[34:35], v[26:27]
	v_and_b32_e32 v35, 0xffff0000, v5
	v_and_b32_e32 v34, 0xffff0000, v1
	v_mov_b32_e32 v36, v29
	v_pk_fma_f32 v[26:27], v[36:37], v[34:35], v[26:27]
	v_lshlrev_b32_e32 v29, 16, v6
	v_lshlrev_b32_e32 v28, 16, v2
	v_mov_b32_e32 v34, v30
	s_waitcnt lgkmcnt(0)
	v_mov_b32_e32 v35, v38
	v_pk_fma_f32 v[26:27], v[34:35], v[28:29], v[26:27]
	v_and_b32_e32 v29, 0xffff0000, v6
	v_and_b32_e32 v28, 0xffff0000, v2
	v_mov_b32_e32 v38, v31
	v_pk_fma_f32 v[26:27], v[38:39], v[28:29], v[26:27]
	v_lshlrev_b32_e32 v29, 16, v7
	v_lshlrev_b32_e32 v28, 16, v3
	v_mov_b32_e32 v30, v32
	v_mov_b32_e32 v31, v40
	v_pk_fma_f32 v[26:27], v[30:31], v[28:29], v[26:27]
	v_and_b32_e32 v29, 0xffff0000, v7
	v_and_b32_e32 v28, 0xffff0000, v3
	v_mov_b32_e32 v40, v33
	v_pk_fma_f32 v[26:27], v[40:41], v[28:29], v[26:27]
	s_waitcnt vmcnt(8)
	v_and_b32_e32 v47, 0xffff0000, v12
	v_add_f32_e32 v23, 0, v26
	v_add_f32_e32 v23, v23, v27
	ds_read_b128 v[26:29], v22 offset:1792
	ds_read_b128 v[30:33], v22 offset:1808
	ds_read_b128 v[34:37], v22 offset:1920
	ds_read_b128 v[38:41], v22 offset:1936
	v_and_b32_e32 v46, 0xffff0000, v8
	v_lshlrev_b32_e32 v43, 16, v12
	v_lshlrev_b32_e32 v42, 16, v8
	s_waitcnt lgkmcnt(1)
	v_mov_b32_e32 v45, v34
	v_mov_b32_e32 v34, v27
	v_mov_b32_e32 v44, v26
	v_pk_mul_f32 v[26:27], v[34:35], v[46:47]
	v_lshlrev_b32_e32 v35, 16, v13
	v_pk_fma_f32 v[26:27], v[44:45], v[42:43], v[26:27]
	v_lshlrev_b32_e32 v34, 16, v9
	v_mov_b32_e32 v42, v28
	v_mov_b32_e32 v43, v36
	v_pk_fma_f32 v[26:27], v[42:43], v[34:35], v[26:27]
	v_and_b32_e32 v35, 0xffff0000, v13
	v_and_b32_e32 v34, 0xffff0000, v9
	v_mov_b32_e32 v36, v29
	v_pk_fma_f32 v[26:27], v[36:37], v[34:35], v[26:27]
	v_lshlrev_b32_e32 v29, 16, v14
	v_lshlrev_b32_e32 v28, 16, v10
	v_mov_b32_e32 v34, v30
	s_waitcnt lgkmcnt(0)
	v_mov_b32_e32 v35, v38
	v_pk_fma_f32 v[26:27], v[34:35], v[28:29], v[26:27]
	v_and_b32_e32 v29, 0xffff0000, v14
	v_and_b32_e32 v28, 0xffff0000, v10
	v_mov_b32_e32 v38, v31
	v_pk_fma_f32 v[26:27], v[38:39], v[28:29], v[26:27]
	v_lshlrev_b32_e32 v29, 16, v15
	v_lshlrev_b32_e32 v28, 16, v11
	v_mov_b32_e32 v30, v32
	v_mov_b32_e32 v31, v40
	v_pk_fma_f32 v[26:27], v[30:31], v[28:29], v[26:27]
	v_and_b32_e32 v29, 0xffff0000, v15
	v_and_b32_e32 v28, 0xffff0000, v11
	v_mov_b32_e32 v40, v33
	v_pk_fma_f32 v[26:27], v[40:41], v[28:29], v[26:27]
	s_nop 0
	v_add_f32_e32 v23, v23, v26
	v_add_f32_e32 v23, v23, v27
	ds_swizzle_b32 v25, v23 offset:swizzle(SWAP,16)
	s_waitcnt lgkmcnt(0)
	v_add_f32_e32 v23, v23, v25
	ds_bpermute_b32 v25, v105, v23
	s_waitcnt lgkmcnt(0)
	v_add_f32_e32 v23, v23, v25
	v_mov_b32_e32 v25, 0xff800000
	s_cmp_lt_u32 s80, 5
	v_mov_b32_e32 v26, 0xff800000
	s_cbranch_scc0 .LBB0_403

.LBB0_409:
	ds_read_b128 v[28:31], v22 offset:2560
	ds_read_b128 v[32:35], v22 offset:2576
	ds_read_b128 v[36:39], v22 offset:2688
	ds_read_b128 v[40:43], v22 offset:2704
	s_waitcnt vmcnt(10)
	v_and_b32_e32 v49, 0xffff0000, v4
	v_and_b32_e32 v48, 0xffff0000, v0
	v_lshlrev_b32_e32 v45, 16, v4
	s_waitcnt lgkmcnt(1)
	v_mov_b32_e32 v47, v36
	v_mov_b32_e32 v36, v29
	v_lshlrev_b32_e32 v44, 16, v0
	v_mov_b32_e32 v46, v28
	v_pk_mul_f32 v[28:29], v[36:37], v[48:49]
	v_lshlrev_b32_e32 v37, 16, v5
	v_pk_fma_f32 v[28:29], v[46:47], v[44:45], v[28:29]
	v_lshlrev_b32_e32 v36, 16, v1
	v_mov_b32_e32 v44, v30
	v_mov_b32_e32 v45, v38
	v_pk_fma_f32 v[28:29], v[44:45], v[36:37], v[28:29]
	v_and_b32_e32 v37, 0xffff0000, v5
	v_and_b32_e32 v36, 0xffff0000, v1
	v_mov_b32_e32 v38, v31
	v_pk_fma_f32 v[28:29], v[38:39], v[36:37], v[28:29]
	v_lshlrev_b32_e32 v31, 16, v6
	v_lshlrev_b32_e32 v30, 16, v2
	v_mov_b32_e32 v36, v32
	s_waitcnt lgkmcnt(0)
	v_mov_b32_e32 v37, v40
	v_pk_fma_f32 v[28:29], v[36:37], v[30:31], v[28:29]
	v_and_b32_e32 v31, 0xffff0000, v6
	v_and_b32_e32 v30, 0xffff0000, v2
	v_mov_b32_e32 v40, v33
	v_pk_fma_f32 v[28:29], v[40:41], v[30:31], v[28:29]
	v_lshlrev_b32_e32 v31, 16, v7
	v_lshlrev_b32_e32 v30, 16, v3
	v_mov_b32_e32 v32, v34
	v_mov_b32_e32 v33, v42
	v_pk_fma_f32 v[28:29], v[32:33], v[30:31], v[28:29]
	v_and_b32_e32 v31, 0xffff0000, v7
	v_and_b32_e32 v30, 0xffff0000, v3
	v_mov_b32_e32 v42, v35
	v_pk_fma_f32 v[28:29], v[42:43], v[30:31], v[28:29]
	s_waitcnt vmcnt(8)
	v_and_b32_e32 v49, 0xffff0000, v12
	v_add_f32_e32 v25, 0, v28
	v_add_f32_e32 v25, v25, v29
	ds_read_b128 v[28:31], v22 offset:2816
	ds_read_b128 v[32:35], v22 offset:2832
	ds_read_b128 v[36:39], v22 offset:2944
	ds_read_b128 v[40:43], v22 offset:2960
	v_and_b32_e32 v48, 0xffff0000, v8
	v_lshlrev_b32_e32 v45, 16, v12
	v_lshlrev_b32_e32 v44, 16, v8
	s_waitcnt lgkmcnt(1)
	v_mov_b32_e32 v47, v36
	v_mov_b32_e32 v36, v29
	v_mov_b32_e32 v46, v28
	v_pk_mul_f32 v[28:29], v[36:37], v[48:49]
	v_lshlrev_b32_e32 v37, 16, v13
	v_pk_fma_f32 v[28:29], v[46:47], v[44:45], v[28:29]
	v_lshlrev_b32_e32 v36, 16, v9
	v_mov_b32_e32 v44, v30
	v_mov_b32_e32 v45, v38
	v_pk_fma_f32 v[28:29], v[44:45], v[36:37], v[28:29]
	v_and_b32_e32 v37, 0xffff0000, v13
	v_and_b32_e32 v36, 0xffff0000, v9
	v_mov_b32_e32 v38, v31
	v_pk_fma_f32 v[28:29], v[38:39], v[36:37], v[28:29]
	v_lshlrev_b32_e32 v31, 16, v14
	v_lshlrev_b32_e32 v30, 16, v10
	v_mov_b32_e32 v36, v32
	s_waitcnt lgkmcnt(0)
	v_mov_b32_e32 v37, v40
	v_pk_fma_f32 v[28:29], v[36:37], v[30:31], v[28:29]
	v_and_b32_e32 v31, 0xffff0000, v14
	v_and_b32_e32 v30, 0xffff0000, v10
	v_mov_b32_e32 v40, v33
	v_pk_fma_f32 v[28:29], v[40:41], v[30:31], v[28:29]
	v_lshlrev_b32_e32 v31, 16, v15
	v_lshlrev_b32_e32 v30, 16, v11
	v_mov_b32_e32 v32, v34
	v_mov_b32_e32 v33, v42
	v_pk_fma_f32 v[28:29], v[32:33], v[30:31], v[28:29]
	v_and_b32_e32 v31, 0xffff0000, v15
	v_and_b32_e32 v30, 0xffff0000, v11
	v_mov_b32_e32 v42, v35
	v_pk_fma_f32 v[28:29], v[42:43], v[30:31], v[28:29]
	s_nop 0
	v_add_f32_e32 v25, v25, v28
	v_add_f32_e32 v25, v25, v29
	ds_swizzle_b32 v27, v25 offset:swizzle(SWAP,16)
	s_waitcnt lgkmcnt(0)
	v_add_f32_e32 v25, v25, v27
	ds_bpermute_b32 v27, v105, v25
	s_waitcnt lgkmcnt(0)
	v_add_f32_e32 v25, v25, v27
.LBB0_410:
	s_lshl_b32 s74, s74, 7
	v_mov_b32_e32 v108, 0xff800000
	s_andn2_b64 vcc, exec, s[52:53]
	v_mov_b32_e32 v27, 0xff800000
	s_cbranch_vccnz .LBB0_412
	ds_read_b128 v[28:31], v22 offset:3072
	ds_read_b128 v[32:35], v22 offset:3088
	ds_read_b128 v[36:39], v22 offset:3200
	ds_read_b128 v[40:43], v22 offset:3216
	s_waitcnt vmcnt(10)
	v_and_b32_e32 v49, 0xffff0000, v4
	v_and_b32_e32 v48, 0xffff0000, v0
	v_lshlrev_b32_e32 v45, 16, v4
	s_waitcnt lgkmcnt(1)
	v_mov_b32_e32 v47, v36
	v_mov_b32_e32 v36, v29
	v_lshlrev_b32_e32 v44, 16, v0
	v_mov_b32_e32 v46, v28
	v_pk_mul_f32 v[28:29], v[36:37], v[48:49]
	v_lshlrev_b32_e32 v37, 16, v5
	v_pk_fma_f32 v[28:29], v[46:47], v[44:45], v[28:29]
	v_lshlrev_b32_e32 v36, 16, v1
	v_mov_b32_e32 v44, v30
	v_mov_b32_e32 v45, v38
	v_pk_fma_f32 v[28:29], v[44:45], v[36:37], v[28:29]
	v_and_b32_e32 v37, 0xffff0000, v5
	v_and_b32_e32 v36, 0xffff0000, v1
	v_mov_b32_e32 v38, v31
	v_pk_fma_f32 v[28:29], v[38:39], v[36:37], v[28:29]
	v_lshlrev_b32_e32 v31, 16, v6
	v_lshlrev_b32_e32 v30, 16, v2
	v_mov_b32_e32 v36, v32
	s_waitcnt lgkmcnt(0)
	v_mov_b32_e32 v37, v40
	v_pk_fma_f32 v[28:29], v[36:37], v[30:31], v[28:29]
	v_and_b32_e32 v31, 0xffff0000, v6
	v_and_b32_e32 v30, 0xffff0000, v2
	v_mov_b32_e32 v40, v33
	v_pk_fma_f32 v[28:29], v[40:41], v[30:31], v[28:29]
	v_lshlrev_b32_e32 v31, 16, v7
	v_lshlrev_b32_e32 v30, 16, v3
	v_mov_b32_e32 v32, v34
	v_mov_b32_e32 v33, v42
	v_pk_fma_f32 v[28:29], v[32:33], v[30:31], v[28:29]
	v_and_b32_e32 v31, 0xffff0000, v7
	v_and_b32_e32 v30, 0xffff0000, v3
	v_mov_b32_e32 v42, v35
	v_pk_fma_f32 v[28:29], v[42:43], v[30:31], v[28:29]
	s_waitcnt vmcnt(8)
	v_and_b32_e32 v49, 0xffff0000, v12
	v_add_f32_e32 v27, 0, v28
	v_add_f32_e32 v27, v27, v29
	ds_read_b128 v[28:31], v22 offset:3328
	ds_read_b128 v[32:35], v22 offset:3344
	ds_read_b128 v[36:39], v22 offset:3456
	ds_read_b128 v[40:43], v22 offset:3472
	v_and_b32_e32 v48, 0xffff0000, v8
	v_lshlrev_b32_e32 v45, 16, v12
	v_lshlrev_b32_e32 v44, 16, v8
	s_waitcnt lgkmcnt(1)
	v_mov_b32_e32 v47, v36
	v_mov_b32_e32 v36, v29
	v_mov_b32_e32 v46, v28
	v_pk_mul_f32 v[28:29], v[36:37], v[48:49]
	v_lshlrev_b32_e32 v37, 16, v13
	v_pk_fma_f32 v[28:29], v[46:47], v[44:45], v[28:29]
	v_lshlrev_b32_e32 v36, 16, v9
	v_mov_b32_e32 v44, v30
	v_mov_b32_e32 v45, v38
	v_pk_fma_f32 v[28:29], v[44:45], v[36:37], v[28:29]
	v_and_b32_e32 v37, 0xffff0000, v13
	v_and_b32_e32 v36, 0xffff0000, v9
	v_mov_b32_e32 v38, v31
	v_pk_fma_f32 v[28:29], v[38:39], v[36:37], v[28:29]
	v_lshlrev_b32_e32 v31, 16, v14
	v_lshlrev_b32_e32 v30, 16, v10
	v_mov_b32_e32 v36, v32
	s_waitcnt lgkmcnt(0)
	v_mov_b32_e32 v37, v40
	v_pk_fma_f32 v[28:29], v[36:37], v[30:31], v[28:29]
	v_and_b32_e32 v31, 0xffff0000, v14
	v_and_b32_e32 v30, 0xffff0000, v10
	v_mov_b32_e32 v40, v33
	v_pk_fma_f32 v[28:29], v[40:41], v[30:31], v[28:29]
	v_lshlrev_b32_e32 v31, 16, v15
	v_lshlrev_b32_e32 v30, 16, v11
	v_mov_b32_e32 v32, v34
	v_mov_b32_e32 v33, v42
	v_pk_fma_f32 v[28:29], v[32:33], v[30:31], v[28:29]
	v_and_b32_e32 v31, 0xffff0000, v15
	v_and_b32_e32 v30, 0xffff0000, v11
	v_mov_b32_e32 v42, v35
	v_pk_fma_f32 v[28:29], v[42:43], v[30:31], v[28:29]
	s_nop 0
	v_add_f32_e32 v22, v27, v28
	v_add_f32_e32 v22, v22, v29
	ds_swizzle_b32 v27, v22 offset:swizzle(SWAP,16)
	s_waitcnt lgkmcnt(0)
	v_add_f32_e32 v22, v22, v27
	ds_bpermute_b32 v27, v105, v22
	s_waitcnt lgkmcnt(0)
	v_add_f32_e32 v27, v22, v27
